# Pool and SGU GEMMs run only the 256-wide nonzero K range of their block-diagonal weights (K 512 -> 256, per-lane DMA offsets shifted by the block)
# baseline (speedup 1.0000x reference)
; __device__ __forceinline__ int opq(int v) { asm volatile("" : "+v"(v)); return v; }
; #define PG8_WAIT_V(n) asm volatile("s_waitcnt vmcnt(" #n ")" ::: "memory")
; #define PG8_BAR __builtin_amdgcn_s_barrier()
; template <class Epi>
; __device__ __forceinline__ void gemm_phase(LAS unsigned char* lds, const Gemm g, const StaticOrder& S, const Epi& E) {
;     const int tid = opq(threadIdx.x), wid = __builtin_amdgcn_readfirstlane(tid >> 6), lane = tid & 63, wr = wid >> 2, wc = wid & 3, fr = lane & 15, fq = lane >> 4;
;     const int K = g.K, nt = K / BK;
;     unsigned voffA[2], voffB[2];
; #pragma unroll
;     for (int i = 0; i < 2; ++i) { int R, C; stage_rc(tid * 16 + i * 8192, R, C); const int Rb = (R & ~31) + perm32(R & 31);
;         voffA[i] = (unsigned)(R * g.lda + C) * 2u; voffB[i] = (unsigned)(Rb * g.ldb + C) * 2u; }
;     const size_t kstep = (size_t)(BK * 2);
;     const size_t hstepA = (size_t)HALF * g.lda * 2, hstepB = (size_t)HALF * g.ldb * 2;
;     const size_t tstepA = 2 * hstepA, tstepB = 2 * hstepB;
;     const unsigned ldsw = (unsigned)wid * 1024u, ldsu = (unsigned)(unsigned long)lds;
;     const int aoff = lds_byte(wr * 64 + fr, fq * 8), boff = lds_byte(wc * 32 + fr, fq * 8);
;     int bbase[2][2];
; #pragma unroll
;     for (int b_ = 0; b_ < 2; ++b_)
; #pragma unroll
;         for (int h_ = 0; h_ < 2; ++h_) bbase[b_][h_] = opq(boff + (4 + b_ * 2 + h_) * HTB);
;     ...
;     Unit cur, nxt; int ui = 0;
;     if (!S.next(0, cur)) return;
;     f32x4 acc[2][2][4][2];
; #pragma unroll
;     for (int a = 0; a < 2; ++a)
; #pragma unroll
;         for (int b = 0; b < 2; ++b)
; #pragma unroll
;             for (int m = 0; m < 4; ++m)
; #pragma unroll
;                 for (int n = 0; n < 2; ++n) acc[a][b][m][n] = (f32x4){0.f, 0.f, 0.f, 0.f};
;     bf16x8 At[4][2], At2[4][2], B0[2][2];
;     const char* cA = (const char*)g.A + (size_t)cur.pm * tstepA; const char* cB = (const char*)g.Bt + (size_t)cur.pn * tstepB;
;     PG8_STAGE(PG8_SB(0, 0), cB, voffB); PG8_STAGE(PG8_SA(0, 0), cA, voffA); PG8_STAGE(PG8_SA(0, 1), cA + hstepA, voffA); PG8_STAGE(PG8_SB(0, 1), cB + hstepB, voffB);
;     if (wr == 1) PG8_BAR;
;     PG8_WAIT_V(2); PG8_BAR;
;     PG8_STAGE(PG8_SB(1, 0), cB + kstep, voffB); PG8_STAGE(PG8_SA(1, 0), cA + kstep, voffA); PG8_STAGE(PG8_SA(1, 1), cA + hstepA + kstep, voffA);
.LBB0_473:
	s_or_b64 exec, exec, s[0:1]
	s_movk_i32 s51, 0x200
	s_mov_b32 s14, 0
	s_cmpk_lg_i32 s34, 0x100
	s_cbranch_scc1 .Lpool_fullk
	s_movk_i32 s51, 0x100
	v_readlane_b32 s14, v253, 26
	s_nop 3
	s_lshl_b32 s14, s14, 9
.Lpool_fullk:
	s_waitcnt lgkmcnt(0)
	s_barrier
	v_mov_b32_e32 v7, v206
	s_ashr_i32 s5, s51, 31
	s_lshr_b32 s5, s5, 26
	v_readfirstlane_b32 s8, v7
	v_lshrrev_b32_e32 v0, 1, v7
	s_ashr_i32 s4, s8, 6
	s_add_i32 s5, s51, s5
	v_and_b32_e32 v0, 24, v0
	v_and_b32_e32 v5, 15, v7
	s_ashr_i32 s28, s5, 6
	v_lshlrev_b32_e32 v1, 1, v0
	s_lshl_b32 s5, s4, 5
	s_and_b32 s9, s5, 0x60
	v_lshl_or_b32 v6, v5, 6, v1
	v_lshlrev_b32_e32 v1, 2, v7
	s_lshl_b32 s5, s9, 7
	v_and_b32_e32 v1, 32, v1
	s_lshl_b32 s2, s66, 9
	s_mov_b32 s3, s36
	v_bitop3_b32 v4, v6, s5, v1 bitop3:0xde
	v_writelane_b32 v255, s89, 4
	s_lshl_b64 s[0:1], s[2:3], 10
	v_or_b32_e32 v2, 0x10000, v4
	v_or_b32_e32 v1, 0x14000, v4
	v_or_b32_e32 v3, 0x18000, v4
	v_or_b32_e32 v4, 0x1c000, v4
	s_and_b64 vcc, exec, s[42:43]
	v_writelane_b32 v255, s95, 2
	s_cbranch_vccnz .LBB0_495
	v_ashrrev_i32_e32 v9, 31, v7
	v_lshrrev_b32_e32 v9, 26, v9
	v_lshlrev_b32_e32 v8, 4, v7
	v_add_u32_e32 v9, v7, v9
	v_bfe_i32 v7, v7, 27, 1
	v_lshrrev_b32_e32 v7, 22, v7
	v_add_u32_e32 v7, v8, v7
	v_and_b32_e32 v7, 0xfffffc00, v7
	v_sub_u32_e32 v7, v8, v7
	v_lshrrev_b32_e32 v10, 4, v7
	v_bitop3_b32 v10, v10, v7, 32 bitop3:0x6c
	v_ashrrev_i32_e32 v7, 31, v7
	v_lshrrev_b32_e32 v7, 26, v7
	v_ashrrev_i32_e32 v9, 6, v9
	v_add_u32_e32 v7, v10, v7
	v_lshlrev_b32_e32 v11, 3, v9
	v_ashrrev_i32_e32 v7, 6, v7
	v_readlane_b32 s5, v252, 62
	v_and_b32_e32 v11, -16, v11
	v_mul_i32_i24_e32 v12, 64, v7
	s_add_u32 s29, s5, s0
	v_readlane_b32 s5, v252, 63
	v_add_u32_e32 v11, v7, v11
	v_sub_u32_e32 v10, v10, v12
	v_mov_b32_e32 v14, 1
	s_addc_u32 s37, s5, s1
	v_lshlrev_b32_e32 v9, 5, v9
	v_ashrrev_i16_sdwa v10, v14, sext(v10) dst_sel:DWORD dst_unused:UNUSED_PAD src0_sel:DWORD src1_sel:BYTE_0
	v_lshlrev_b32_e32 v12, 1, v11
	v_lshrrev_b32_e32 v13, 2, v11
	v_and_b32_e32 v7, 3, v7
	s_mov_b32 s5, 0x3fffe0
	v_and_b32_e32 v9, 32, v9
	v_bfe_i32 v10, v10, 0, 16
	v_and_b32_e32 v12, 24, v12
	v_and_b32_e32 v13, 4, v13
	v_and_or_b32 v7, v11, s5, v7
	v_or3_b32 v7, v7, v13, v12
	v_add_lshl_u32 v9, v9, v10, 1
	v_lshl_add_u32 v129, v7, 10, v9
	v_add_u32_e32 v129, s14, v129
	v_add_u32_e32 v7, 0x2000, v8
	v_ashrrev_i32_e32 v8, 31, v7
	v_lshrrev_b32_e32 v8, 22, v8
	v_add_u32_e32 v8, v7, v8
	v_ashrrev_i32_e32 v8, 10, v8
	v_lshl_add_u32 v128, v11, 10, v9
	v_add_u32_e32 v128, s14, v128
	v_mul_i32_i24_e32 v9, 0x400, v8
	v_sub_u32_e32 v7, v7, v9
	v_lshrrev_b32_e32 v9, 4, v7
	v_bitop3_b32 v7, v9, v7, 32 bitop3:0x6c
	v_ashrrev_i32_e32 v10, 31, v7
	v_lshrrev_b32_e32 v10, 26, v10
	v_lshlrev_b32_e32 v9, 3, v8
	v_add_u32_e32 v10, v7, v10
	v_and_b32_e32 v9, -16, v9
	v_ashrrev_i32_e32 v11, 6, v10
	v_and_b32_e32 v10, 0xc0, v10
	v_add_u32_e32 v9, v11, v9
	v_sub_u32_e32 v7, v7, v10
	s_ashr_i32 s10, s8, 8
	s_lshl_b32 s4, s4, 10
	v_readlane_b32 s6, v253, 27
	v_lshlrev_b32_e32 v8, 5, v8
	v_ashrrev_i16_sdwa v7, v14, sext(v7) dst_sel:DWORD dst_unused:UNUSED_PAD src0_sel:DWORD src1_sel:BYTE_0
	v_lshlrev_b32_e32 v10, 1, v9
	v_lshrrev_b32_e32 v12, 2, v9
	v_and_b32_e32 v11, 3, v11
	v_readlane_b32 s7, v253, 28
	s_add_u32 s80, s29, s6
	v_and_b32_e32 v8, 32, v8
	v_bfe_i32 v7, v7, 0, 16
	v_and_b32_e32 v10, 24, v10
	v_and_b32_e32 v12, 4, v12
	v_and_or_b32 v11, v9, s5, v11
	s_addc_u32 s81, s37, s7
	s_add_i32 s47, s4, 0
	v_or3_b32 v10, v11, v12, v10
	v_add_lshl_u32 v7, v8, v7, 1
	s_add_i32 s48, s47, 0x10000
	s_mov_b32 m0, s48
	s_nop 0
	global_load_lds_dwordx4 v129, s[80:81]
	v_lshl_add_u32 v131, v10, 10, v7
	v_add_u32_e32 v131, s14, v131
	s_add_i32 s49, s47, 0x12000
	s_mov_b32 m0, s49
	s_nop 0
	global_load_lds_dwordx4 v131, s[80:81]
	v_readlane_b32 s4, v253, 36
	v_readlane_b32 s5, v253, 37
	s_mov_b32 m0, s47
	s_nop 0
	global_load_lds_dwordx4 v128, s[4:5]
	v_lshl_add_u32 v130, v9, 10, v7
	v_add_u32_e32 v130, s14, v130
	s_add_i32 s50, s47, 0x2000
	s_mov_b32 m0, s50
	s_nop 0
	global_load_lds_dwordx4 v130, s[4:5]
	v_readlane_b32 s4, v253, 32
	s_add_i32 s52, s47, 0x4000
	v_readlane_b32 s5, v253, 33
	s_mov_b32 m0, s52
	s_nop 0
	global_load_lds_dwordx4 v128, s[4:5]
	s_add_i32 s53, s47, 0x6000
	s_add_i32 s54, s47, 0x14000
	s_mov_b32 m0, s53
	s_nop 0
	global_load_lds_dwordx4 v130, s[4:5]
	s_add_u32 s4, s80, 0x20000
	v_writelane_b32 v255, s42, 6
	s_addc_u32 s5, s81, 0
	s_mov_b32 m0, s54
	s_nop 0
	global_load_lds_dwordx4 v129, s[4:5]
	s_add_i32 s55, s47, 0x16000
	v_writelane_b32 v255, s43, 7
	s_mov_b32 m0, s55
	s_nop 0
	global_load_lds_dwordx4 v131, s[4:5]
	v_writelane_b32 v255, s66, 0
	s_cmp_eq_u32 s10, 1
	v_mov_b32_e32 v209, 1
	v_writelane_b32 v255, s67, 1
	s_cselect_b64 s[4:5], -1, 0
	s_cmp_lg_u32 s10, 1
	s_cbranch_scc1 .LBB0_476
	s_barrier

; __device__ __forceinline__ int opq(int v) { asm volatile("" : "+v"(v)); return v; }
; #define PG8_WAIT_V(n) asm volatile("s_waitcnt vmcnt(" #n ")" ::: "memory")
; #define PG8_BAR __builtin_amdgcn_s_barrier()
; template <class Epi>
; __device__ __forceinline__ void gemm_phase(LAS unsigned char* lds, const Gemm g, const StaticOrder& S, const Epi& E) {
;     const int tid = opq(threadIdx.x), wid = __builtin_amdgcn_readfirstlane(tid >> 6), lane = tid & 63, wr = wid >> 2, wc = wid & 3, fr = lane & 15, fq = lane >> 4;
;     const int K = g.K, nt = K / BK;
;     unsigned voffA[2], voffB[2];
; #pragma unroll
;     for (int i = 0; i < 2; ++i) { int R, C; stage_rc(tid * 16 + i * 8192, R, C); const int Rb = (R & ~31) + perm32(R & 31);
;         voffA[i] = (unsigned)(R * g.lda + C) * 2u; voffB[i] = (unsigned)(Rb * g.ldb + C) * 2u; }
;     const size_t kstep = (size_t)(BK * 2);
;     const size_t hstepA = (size_t)HALF * g.lda * 2, hstepB = (size_t)HALF * g.ldb * 2;
;     const size_t tstepA = 2 * hstepA, tstepB = 2 * hstepB;
;     const unsigned ldsw = (unsigned)wid * 1024u, ldsu = (unsigned)(unsigned long)lds;
;     const int aoff = lds_byte(wr * 64 + fr, fq * 8), boff = lds_byte(wc * 32 + fr, fq * 8);
;     int bbase[2][2];
; #pragma unroll
;     for (int b_ = 0; b_ < 2; ++b_)
; #pragma unroll
;         for (int h_ = 0; h_ < 2; ++h_) bbase[b_][h_] = opq(boff + (4 + b_ * 2 + h_) * HTB);
;     ...
;     Unit cur, nxt; int ui = 0;
;     if (!S.next(0, cur)) return;
;     f32x4 acc[2][2][4][2];
; #pragma unroll
;     for (int a = 0; a < 2; ++a)
; #pragma unroll
;         for (int b = 0; b < 2; ++b)
; #pragma unroll
;             for (int m = 0; m < 4; ++m)
; #pragma unroll
;                 for (int n = 0; n < 2; ++n) acc[a][b][m][n] = (f32x4){0.f, 0.f, 0.f, 0.f};
;     bf16x8 At[4][2], At2[4][2], B0[2][2];
;     const char* cA = (const char*)g.A + (size_t)cur.pm * tstepA; const char* cB = (const char*)g.Bt + (size_t)cur.pn * tstepB;
;     PG8_STAGE(PG8_SB(0, 0), cB, voffB); PG8_STAGE(PG8_SA(0, 0), cA, voffA); PG8_STAGE(PG8_SA(0, 1), cA + hstepA, voffA); PG8_STAGE(PG8_SB(0, 1), cB + hstepB, voffB);
;     if (wr == 1) PG8_BAR;
;     PG8_WAIT_V(2); PG8_BAR;
;     PG8_STAGE(PG8_SB(1, 0), cB + kstep, voffB); PG8_STAGE(PG8_SA(1, 0), cA + kstep, voffA); PG8_STAGE(PG8_SA(1, 1), cA + hstepA + kstep, voffA);
.LBB0_495:
	v_mov_b32_e32 v6, v206
	s_and_b64 vcc, exec, s[42:43]
	v_readfirstlane_b32 s10, v6
	v_lshrrev_b32_e32 v0, 1, v6
	s_ashr_i32 s4, s10, 6
	v_and_b32_e32 v0, 24, v0
	v_and_b32_e32 v139, 15, v6
	v_lshlrev_b32_e32 v1, 1, v0
	s_lshl_b32 s5, s4, 5
	s_and_b32 s12, s5, 0x60
	v_lshl_or_b32 v5, v139, 6, v1
	v_lshlrev_b32_e32 v1, 2, v6
	s_lshl_b32 s5, s12, 7
	v_and_b32_e32 v1, 32, v1
	v_bitop3_b32 v4, v5, s5, v1 bitop3:0xde
	v_or_b32_e32 v2, 0x10000, v4
	v_or_b32_e32 v1, 0x14000, v4
	v_or_b32_e32 v3, 0x18000, v4
	v_or_b32_e32 v4, 0x1c000, v4
	s_cbranch_vccnz .LBB0_517
	s_mov_b32 s9, 0
	s_cmpk_lg_i32 s34, 0x100
	s_cbranch_scc1 .Lsgu_fullk
	v_readlane_b32 s9, v254, 43
	s_nop 3
	s_lshl_b32 s9, s9, 9
.Lsgu_fullk:
	v_ashrrev_i32_e32 v8, 31, v6
	v_lshrrev_b32_e32 v8, 26, v8
	v_lshlrev_b32_e32 v7, 4, v6
	v_add_u32_e32 v8, v6, v8
	v_bfe_i32 v6, v6, 27, 1
	v_lshrrev_b32_e32 v6, 22, v6
	v_add_u32_e32 v6, v7, v6
	v_and_b32_e32 v6, 0xfffffc00, v6
	v_sub_u32_e32 v6, v7, v6
	v_lshrrev_b32_e32 v9, 4, v6
	v_bitop3_b32 v9, v9, v6, 32 bitop3:0x6c
	v_ashrrev_i32_e32 v6, 31, v6
	v_lshrrev_b32_e32 v6, 26, v6
	v_ashrrev_i32_e32 v8, 6, v8
	v_add_u32_e32 v6, v9, v6
	v_lshlrev_b32_e32 v10, 3, v8
	v_ashrrev_i32_e32 v6, 6, v6
	v_readlane_b32 s5, v253, 0
	v_and_b32_e32 v10, -16, v10
	v_mul_i32_i24_e32 v11, 64, v6
	s_add_u32 s29, s5, s0
	v_readlane_b32 s0, v253, 1
	v_add_u32_e32 v10, v6, v10
	v_sub_u32_e32 v9, v9, v11
	v_mov_b32_e32 v13, 1
	s_addc_u32 s47, s0, s1
	v_lshlrev_b32_e32 v8, 5, v8
	v_ashrrev_i16_sdwa v9, v13, sext(v9) dst_sel:DWORD dst_unused:UNUSED_PAD src0_sel:DWORD src1_sel:BYTE_0
	v_lshlrev_b32_e32 v11, 1, v10
	v_lshrrev_b32_e32 v12, 2, v10
	v_and_b32_e32 v6, 3, v6
	s_mov_b32 s0, 0x3fffe0
	v_and_b32_e32 v8, 32, v8
	v_bfe_i32 v9, v9, 0, 16
	v_and_b32_e32 v11, 24, v11
	v_and_b32_e32 v12, 4, v12
	v_and_or_b32 v6, v10, s0, v6
	v_or3_b32 v6, v6, v12, v11
	v_add_lshl_u32 v8, v8, v9, 1
	v_lshl_add_u32 v141, v6, 10, v8
	v_add_u32_e32 v141, s9, v141
	v_add_u32_e32 v6, 0x2000, v7
	v_ashrrev_i32_e32 v7, 31, v6
	v_lshrrev_b32_e32 v7, 22, v7
	v_add_u32_e32 v7, v6, v7
	v_ashrrev_i32_e32 v7, 10, v7
	v_lshl_add_u32 v140, v10, 10, v8
	v_add_u32_e32 v140, s9, v140
	v_mul_i32_i24_e32 v8, 0x400, v7
	v_sub_u32_e32 v6, v6, v8
	v_lshrrev_b32_e32 v8, 4, v6
	v_bitop3_b32 v6, v8, v6, 32 bitop3:0x6c
	v_ashrrev_i32_e32 v9, 31, v6
	v_lshrrev_b32_e32 v9, 26, v9
	v_lshlrev_b32_e32 v8, 3, v7
	v_add_u32_e32 v9, v6, v9
	v_and_b32_e32 v8, -16, v8
	v_ashrrev_i32_e32 v10, 6, v9
	v_and_b32_e32 v9, 0xc0, v9
	v_add_u32_e32 v8, v10, v8
	v_sub_u32_e32 v6, v6, v9
	v_and_b32_e32 v10, 3, v10
	v_lshlrev_b32_e32 v7, 5, v7
	v_ashrrev_i16_sdwa v6, v13, sext(v6) dst_sel:DWORD dst_unused:UNUSED_PAD src0_sel:DWORD src1_sel:BYTE_0
	v_lshlrev_b32_e32 v9, 1, v8
	v_lshrrev_b32_e32 v11, 2, v8
	v_and_or_b32 v10, v8, s0, v10
	s_lshl_b32 s0, s4, 10
	v_and_b32_e32 v7, 32, v7
	v_bfe_i32 v6, v6, 0, 16
	v_and_b32_e32 v9, 24, v9
	v_and_b32_e32 v11, 4, v11
	s_add_i32 s84, s0, 0
	v_readlane_b32 s0, v254, 50
	s_load_dwordx2 s[6:7], s[56:57], 0xa0
	v_or3_b32 v9, v10, v11, v9
	v_add_lshl_u32 v6, v7, v6, 1
	s_add_i32 s85, s84, 0x10000
	v_readlane_b32 s1, v254, 51
	s_mov_b32 m0, s85
	s_nop 0
	global_load_lds_dwordx4 v141, s[0:1]
	v_lshl_add_u32 v143, v9, 10, v6
	v_add_u32_e32 v143, s9, v143
	s_ashr_i32 s8, s10, 8
	s_add_i32 s86, s84, 0x12000
	s_mov_b32 m0, s86
	s_nop 0
	global_load_lds_dwordx4 v143, s[0:1]
	v_readlane_b32 s0, v254, 45
	v_readlane_b32 s1, v254, 46
	s_add_u32 s4, s29, s0
	s_addc_u32 s5, s47, s1
	s_mov_b32 m0, s84
	s_nop 0
	global_load_lds_dwordx4 v140, s[4:5]
	s_add_i32 s87, s84, 0x2000
	s_add_i32 s88, s84, 0x4000
	v_lshl_add_u32 v142, v8, 10, v6
	v_add_u32_e32 v142, s9, v142
	s_mov_b32 m0, s87
	s_nop 0
	global_load_lds_dwordx4 v142, s[4:5]
	s_add_u32 s0, s4, 0x20000
	s_addc_u32 s1, s5, 0
	s_mov_b32 m0, s88
	s_nop 0
	global_load_lds_dwordx4 v140, s[0:1]
	s_add_i32 s89, s84, 0x6000
	s_mov_b32 m0, s89
	s_nop 0
	global_load_lds_dwordx4 v142, s[0:1]
	v_readlane_b32 s14, v254, 48
	s_add_i32 s90, s84, 0x14000
	v_readlane_b32 s15, v254, 49
	s_mov_b32 m0, s90
	s_nop 0
	global_load_lds_dwordx4 v141, s[14:15]
	s_add_i32 s91, s84, 0x16000
	s_mov_b32 m0, s91
	s_nop 0
	global_load_lds_dwordx4 v143, s[14:15]
	s_cmp_eq_u32 s8, 1
	v_mov_b32_e32 v209, 1
	s_cselect_b64 s[0:1], -1, 0
	s_cmp_lg_u32 s8, 1
	s_cbranch_scc1 .LBB0_498
	s_barrier
